# attn1 tile loads: SGPR base + 32-bit lane offset (saddr form), bases advanced by SALU; removes 64-bit VALU address math per step
# speedup vs baseline: 1.0465x; 1.0020x over previous
; #define LAS __attribute__((address_space(3)))
; #define ATT_GLOAD(t_) do { const size_t row_ = (size_t)(A.k_row0 + 64 * (t_)); \
;         kreg = *(const u32x4*)(A.K + (row_ + lkey) * A.k_stride + 8 * lpc); vreg = *(const u32x4*)(A.V + (row_ + lkey) * A.v_stride + 8 * lpc); \
;         if (DQ == 96 && tid < 256) k2reg = *(const u32x4*)(A.K2 + (row_ + l2key) * 32 + 8 * l2pc); } while (0)
; #define ATT_LSTORE(buf_) do { LAS unsigned char* kb_ = lds + (buf_) * KBUF; LAS unsigned char* vb_ = lds + 2 * KBUF + (buf_) * VBUF; \
;         *(LAS u32x4*)(kb_ + (lkey * KSTR + 8 * lpc) * 2) = kreg; *(LAS u32x4*)(vb_ + (lkey * VROW + 8 * lpc) * 2) = vreg; \
;         if (DQ == 96 && tid < 256) *(LAS u32x4*)(kb_ + (l2key * KSTR + 64 + 8 * l2pc) * 2) = k2reg; } while (0)
; template <int DQ, bool BIAS, bool TAIL>
; __device__ __forceinline__ void attn_item(const AttnItem& A, LAS unsigned char* lds, int wave_s_) {
;     ...
;     f32x16 o[2][2];
;     float zinit = 0.f; asm volatile("" : "+v"(zinit));
;     const f32x16 zero16v = {0.f, 0.f, 0.f, 0.f, 0.f, 0.f, 0.f, 0.f, 0.f, 0.f, 0.f, 0.f, 0.f, 0.f, 0.f, 0.f};
;     float mref[2] = {A.m0, A.m0};
; #pragma unroll
;     for (int qb = 0; qb < 2; ++qb)
; #pragma unroll
;         for (int i = 0; i < 16; ++i) { o[0][qb][i] = zinit; o[1][qb][i] = zinit; }
;     float lrun[2] = {hi == 0 ? A.l0 : 0.f, hi == 0 ? A.l0 : 0.f};
;     bool first = A.l0 == 0.f;
;     const int lkey = tid >> 3, lpc = tid & 7, l2key = tid >> 2, l2pc = tid & 3;
;     u32x4 kreg, k2reg, vreg;
;     ...
;     ATT_GLOAD(A.t_lo); ATT_LSTORE(0);
;     __syncthreads();
;     const int i16 = lane & 15, vlane_off = ((4 * hi + (i16 >> 2)) * VROW + 16 * ((lane >> 4) & 1) + 4 * (i16 & 3)) * 2;
;     const int koff = (r32 * KSTR + 8 * hi) * 2;
;     if (w < 4) __builtin_amdgcn_s_setprio(2);
;     int buf = 0;
;     for (int t = A.t_lo; t <= A.t_hi; ++t) {
;         const bool more = t < A.t_hi;
;         const bool act = t >= wlo && t <= whi;
;         const LAS unsigned char* kb = lds + buf * KBUF + koff; const LAS unsigned char* vb = lds + 2 * KBUF + buf * VBUF + vlane_off;
;         bf16x8 kf[NKK];
;         if (act) {
; #pragma unroll
;             for (int kk = 0; kk < NKK; ++kk) kf[kk] = *(const LAS bf16x8*)(kb + (16 * kk) * 2);
;         }
;         if (more) ATT_GLOAD(t + 1);
.LBB0_1472:
	v_lshlrev_b32_e32 v222, 2, v12
	v_lshrrev_b32_e32 v1, 2, v11
	v_and_b32_e32 v2, 16, v11
	v_lshlrev_b32_e32 v3, 2, v11
	v_and_b32_e32 v17, 63, v11
	v_and_or_b32 v1, v1, 3, v222
	v_and_or_b32 v2, v3, 12, v2
	s_movk_i32 s1, 0x48
	v_mad_u32_u24 v18, v1, s1, v2
	v_mul_u32_u24_e32 v19, 0xd0, v220
	v_mov_b64_e32 v[14:15], 0
	v_cmp_gt_u32_e64 s[4:5], 32, v17
	v_mov_b32_e32 v17, v197
	v_mov_b32_e32 v1, v0
	v_mov_b64_e32 v[2:3], 0
	v_mov_b64_e32 v[4:5], 0
	v_mov_b64_e32 v[6:7], 0
	v_mov_b64_e32 v[8:9], 0
	v_mov_b64_e32 v[10:11], 0
	v_mov_b64_e32 v[12:13], 0
	v_add3_u32 v228, 0, v196, v19
	v_lshl_add_u32 v227, v18, 1, 0
	v_lshl_add_u32 v214, v206, 11, v16
	s_nop 0
	v_mov_b32_e32 v211, v197
	v_mov_b32_e32 v196, v197
	v_mov_b64_e32 v[46:47], v[14:15]
	v_mov_b64_e32 v[30:31], v[14:15]
	v_mov_b64_e32 v[62:63], v[14:15]
	s_min_i32 s1, s20, s66
	v_lshl_add_u32 v218, v208, 6, v210
	s_add_i32 s89, s72, 64
	s_lshl_b32 s32, s89, 11
	s_add_u32 s90, s46, s32
	s_addc_u32 s91, s47, 0
	s_add_u32 s92, s48, s32
	s_addc_u32 s93, s49, 0
	s_lshl_b32 s32, s89, 6
	s_add_u32 s98, s40, s32
	s_addc_u32 s99, s41, 0
	s_mov_b32 s21, 0
	s_mov_b64 s[16:17], -1
	s_mov_b64 s[100:101], -1
	v_mov_b32_e32 v223, 0
	v_mov_b64_e32 v[44:45], v[12:13]
	v_mov_b64_e32 v[42:43], v[10:11]
	v_mov_b64_e32 v[40:41], v[8:9]
	v_mov_b64_e32 v[38:39], v[6:7]
	v_mov_b64_e32 v[36:37], v[4:5]
	v_mov_b64_e32 v[34:35], v[2:3]
	v_mov_b64_e32 v[32:33], v[0:1]
	v_mov_b64_e32 v[28:29], v[12:13]
	v_mov_b64_e32 v[26:27], v[10:11]
	v_mov_b64_e32 v[24:25], v[8:9]
	v_mov_b64_e32 v[22:23], v[6:7]
	v_mov_b64_e32 v[20:21], v[4:5]
	v_mov_b64_e32 v[18:19], v[2:3]
	v_mov_b64_e32 v[16:17], v[0:1]
	v_mov_b64_e32 v[60:61], v[12:13]
	v_mov_b64_e32 v[58:59], v[10:11]
	v_mov_b64_e32 v[56:57], v[8:9]
	v_mov_b64_e32 v[54:55], v[6:7]
	v_mov_b64_e32 v[52:53], v[4:5]
	v_mov_b64_e32 v[50:51], v[2:3]
	v_mov_b64_e32 v[48:49], v[0:1]
	v_mov_b32_e32 v211, 0
	s_mov_b32 s22, 0
	v_mov_b64_e32 v[212:213], v[196:197]
	s_branch .LBB0_1474
.LBB0_1473:
	s_or_b64 exec, exec, s[8:9]
	s_add_i32 s22, s22, 1
	s_add_u32 s90, s90, 0x20000
	s_addc_u32 s91, s91, 0
	s_add_u32 s92, s92, 0x20000
	s_addc_u32 s93, s93, 0
	s_add_u32 s98, s98, 0x1000
	s_addc_u32 s99, s99, 0
	s_cmp_eq_u32 s66, s22
	s_waitcnt lgkmcnt(0)
	s_barrier
	s_cbranch_scc1 .LBB0_1486

; #define ATT_GLOAD(t_) do { const size_t row_ = (size_t)(A.k_row0 + 64 * (t_)); \
;         kreg = *(const u32x4*)(A.K + (row_ + lkey) * A.k_stride + 8 * lpc); vreg = *(const u32x4*)(A.V + (row_ + lkey) * A.v_stride + 8 * lpc); \
;         if (DQ == 96 && tid < 256) k2reg = *(const u32x4*)(A.K2 + (row_ + l2key) * 32 + 8 * l2pc); } while (0)
; template <int DQ, bool BIAS, bool TAIL>
; __device__ __forceinline__ void attn_item(const AttnItem& A, LAS unsigned char* lds, int wave_s_) {
;     ...
;         if (more) ATT_GLOAD(t + 1);
.LBB0_1476:
	global_load_dwordx4 v[152:155], v214, s[90:91]
	global_load_dwordx4 v[148:151], v214, s[92:93]
	s_and_saveexec_b64 s[10:11], s[6:7]
	s_cbranch_execz .LBB0_1478
	global_load_dwordx4 v[144:147], v218, s[98:99]
